# P19+P20: adaLN GEMV of layers 1-3 moved from phase 0 to GEMM1's idle blocks (phase-0 code re-entered), GEMV K-loop trips fused (16 loads in flight), silu table only on GEMV blocks; branch islands for
# baseline (speedup 1.0000x reference)
_Z14fwd_megakernel6Paramsiii:
	s_load_dwordx4 s[52:55], s[0:1], 0xa0
	s_load_dwordx2 s[72:73], s[0:1], 0xb0
	s_waitcnt lgkmcnt(0)
	s_load_dword s55, s[0:1], 0xb8
	s_add_u32 s4, s0, 0xb0
	s_addc_u32 s5, s1, 0
	v_and_b32_e32 v204, 0x3ff, v0
	v_writelane_b32 v253, s4, 0
	s_movk_i32 s3, 0x3ff
	v_mov_b32_e32 v1, v204
	v_writelane_b32 v253, s5, 1
	v_mov_b32_e32 v247, 0
	s_cmp_lg_u32 s54, 2
	s_cbranch_scc1 .LBB0_12
	v_lshrrev_b32_e32 v1, 20, v0
	v_lshrrev_b32_e32 v0, 10, v0
	v_or_b32_e32 v0, v0, v1
	v_and_or_b32 v0, v0, s3, v204
	v_cmp_eq_u32_e32 vcc, 0, v0
	s_waitcnt lgkmcnt(0)
	s_barrier
	s_and_saveexec_b64 s[4:5], vcc
	s_cbranch_execz .LBB0_11
	v_readlane_b32 s6, v253, 0
	v_readlane_b32 s7, v253, 1
	buffer_wbl2 sc1
	s_load_dwordx2 s[6:7], s[6:7], 0x58
	v_mov_b32_e32 v2, 0
	s_mov_b64 s[8:9], exec
	v_mbcnt_lo_u32_b32 v1, s8, 0
	v_mbcnt_hi_u32_b32 v1, s9, v1
	s_waitcnt lgkmcnt(0)
	global_load_dword v0, v2, s[6:7] offset:40
	v_cmp_eq_u32_e32 vcc, 0, v1
	s_and_saveexec_b64 s[10:11], vcc
	s_cbranch_execz .LBB0_4
	s_bcnt1_i32_b64 s3, s[8:9]
	v_mov_b32_e32 v3, s3
	global_atomic_add v3, v2, v3, s[6:7] offset:32 sc0

.Lgemv_entry:
	s_load_dwordx8 s[12:19], s[0:1], 0x10
	s_load_dwordx4 s[20:23], s[0:1], 0x30
	s_load_dwordx2 s[34:35], s[0:1], 0x68
	s_load_dwordx2 s[30:31], s[0:1], 0x80
	s_mov_b64 s[4:5], s[64:65]
	s_mov_b64 s[28:29], s[66:67]
	v_mov_b32_e32 v22, v204
	v_readfirstlane_b32 s3, v247
	s_mul_i32 s3, s3, 0x90
	s_add_i32 s3, s3, 0x2f
	s_cmp_gt_i32 s2, s3
	s_cselect_b32 s3, 0, 0x1800
	s_nop 0
	v_cmp_gt_i32_e32 vcc, s3, v22
	s_and_saveexec_b64 s[4:5], vcc
	s_cbranch_execz .LBB0_25
	v_lshl_add_u32 v4, v22, 2, 0
	s_mov_b64 s[6:7], 0
	s_movk_i32 s3, 0x7ff
	s_movk_i32 s10, 0xf800
	v_mov_b32_e32 v1, 0
	s_movk_i32 s11, 0x15ff
	v_mov_b32_e32 v5, v22
	s_branch .LBB0_21

.LBB0_25:
	s_or_b64 exec, exec, s[4:5]
	s_load_dwordx4 s[8:11], s[0:1], 0x50
	v_readfirstlane_b32 s3, v247
	s_mul_i32 s3, s3, 0x90
	s_add_i32 s3, s3, 0x2f
	s_cmp_gt_i32 s2, s3
	s_waitcnt lgkmcnt(0)
	s_barrier
	s_cbranch_scc1 .LBB0_35
	v_lshlrev_b32_e32 v0, 2, v22
	v_ashrrev_i32_e32 v1, 6, v22
	v_and_b32_e32 v0, 0xfc, v0
	s_movk_i32 s3, 0xc00
	v_lshlrev_b32_e32 v12, 7, v1
	v_lshl_add_u32 v23, v1, 9, 0
	v_mul_lo_u32 v1, v1, s3
	v_lshlrev_b32_e32 v2, 2, v0
	v_add3_u32 v24, 0, v1, v2
	v_mov_b32_e32 v1, 2
	v_mov_b32_e32 v15, 0
	v_lshlrev_b32_sdwa v14, v1, v22 dst_sel:DWORD dst_unused:UNUSED_PAD src0_sel:DWORD src1_sel:BYTE_0
	s_movk_i32 s3, 0x300
	v_lshl_add_u64 v[2:3], s[28:29], 0, v[14:15]
	s_mov_b64 s[6:7], 0x7000000
	v_ashrrev_i32_e32 v13, 31, v12
	v_cmp_gt_i32_e64 s[4:5], s3, v22
	s_movk_i32 s3, 0xff
	v_add_u32_e32 v25, 0, v14
	v_lshl_add_u64 v[16:17], v[2:3], 0, s[6:7]
	s_movk_i32 s33, 0x6000
	v_mov_b64_e32 v[18:19], s[20:21]
	v_lshlrev_b32_e32 v14, 2, v0
	s_mov_b32 s36, 0xc000
	s_mov_b32 s37, 0x12000
	s_mov_b32 s38, 0x18000
	s_mov_b32 s39, 0x1e000
	s_mov_b32 s40, 0x24000
	s_mov_b32 s41, 0x2a000
	s_movk_i32 s42, 0x1800
	s_mov_b32 s43, s2
	s_branch .LBB0_28

.LBB0_29:
	v_lshl_add_u64 v[32:33], v[20:21], 0, s[18:19]
	v_add_co_u32_e32 v34, vcc, s33, v32
	global_load_dwordx4 v[28:31], v[32:33], off nt
	s_nop 0
	v_addc_co_u32_e32 v35, vcc, 0, v33, vcc
	v_add_co_u32_e32 v36, vcc, s36, v32
	s_add_u32 s18, s18, 0x30000
	s_nop 0
	v_addc_co_u32_e32 v37, vcc, 0, v33, vcc
	v_add_co_u32_e32 v40, vcc, s37, v32
	s_addc_u32 s19, s19, 0
	s_nop 0
	v_addc_co_u32_e32 v41, vcc, 0, v33, vcc
	v_add_co_u32_e32 v44, vcc, s38, v32
	s_cmp_eq_u32 s18, 0x300000
	s_nop 0
	v_addc_co_u32_e32 v45, vcc, 0, v33, vcc
	v_add_co_u32_e32 v48, vcc, s39, v32
	s_nop 1
	v_addc_co_u32_e32 v49, vcc, 0, v33, vcc
	v_add_co_u32_e32 v52, vcc, s40, v32
	s_nop 1
	v_addc_co_u32_e32 v53, vcc, 0, v33, vcc
	v_add_co_u32_e32 v56, vcc, s41, v32
	s_nop 1
	v_addc_co_u32_e32 v57, vcc, 0, v33, vcc
	global_load_dwordx4 v[32:35], v[34:35], off nt
	s_nop 0
	global_load_dwordx4 v[36:39], v[36:37], off nt
	s_nop 0
	global_load_dwordx4 v[40:43], v[40:41], off nt
	s_nop 0
	global_load_dwordx4 v[44:47], v[44:45], off nt
	s_nop 0
	global_load_dwordx4 v[48:51], v[48:49], off nt
	s_nop 0
	global_load_dwordx4 v[52:55], v[52:53], off nt
	s_nop 0
	global_load_dwordx4 v[56:59], v[56:57], off nt
	v_lshl_add_u64 v[104:105], v[20:21], 0, s[18:19]
	v_add_co_u32_e32 v106, vcc, s33, v104
	global_load_dwordx4 v[100:103], v[104:105], off nt
	s_nop 0
	v_addc_co_u32_e32 v107, vcc, 0, v105, vcc
	v_add_co_u32_e32 v108, vcc, s36, v104
	s_add_u32 s18, s18, 0x30000
	s_nop 0
	v_addc_co_u32_e32 v109, vcc, 0, v105, vcc
	v_add_co_u32_e32 v112, vcc, s37, v104
	s_addc_u32 s19, s19, 0
	s_nop 0
	v_addc_co_u32_e32 v113, vcc, 0, v105, vcc
	v_add_co_u32_e32 v116, vcc, s38, v104
	s_cmp_eq_u32 s18, 0x300000
	s_nop 0
	v_addc_co_u32_e32 v117, vcc, 0, v105, vcc
	v_add_co_u32_e32 v120, vcc, s39, v104
	s_nop 1
	v_addc_co_u32_e32 v121, vcc, 0, v105, vcc
	v_add_co_u32_e32 v124, vcc, s40, v104
	s_nop 1
	v_addc_co_u32_e32 v125, vcc, 0, v105, vcc
	v_add_co_u32_e32 v128, vcc, s41, v104
	s_nop 1
	v_addc_co_u32_e32 v129, vcc, 0, v105, vcc
	global_load_dwordx4 v[104:107], v[106:107], off nt
	s_nop 0
	global_load_dwordx4 v[108:111], v[108:109], off nt
	s_nop 0
	global_load_dwordx4 v[112:115], v[112:113], off nt
	s_nop 0
	global_load_dwordx4 v[116:119], v[116:117], off nt
	s_nop 0
	global_load_dwordx4 v[120:123], v[120:121], off nt
	s_nop 0
	global_load_dwordx4 v[124:127], v[124:125], off nt
	s_nop 0
	global_load_dwordx4 v[128:131], v[128:129], off nt
	ds_read_b128 v[60:63], v26
	ds_read_b128 v[64:67], v26 offset:16
	ds_read_b128 v[68:71], v26 offset:8192
	ds_read_b128 v[72:75], v26 offset:8208
	ds_read_b128 v[76:79], v26 offset:16384
	ds_read_b128 v[80:83], v26 offset:16400
	s_waitcnt lgkmcnt(0)
	v_mov_b32_e32 v84, v63
	s_waitcnt lgkmcnt(3)
	v_mov_b32_e32 v86, v71
	v_mov_b32_e32 v90, v67
	s_waitcnt lgkmcnt(1)
	v_mov_b32_e32 v88, v79
	v_mov_b32_e32 v92, v75
	s_waitcnt lgkmcnt(0)
	v_mov_b32_e32 v94, v83
	v_add_u32_e32 v26, 32, v26
	ds_read_b128 v[132:135], v26
	ds_read_b128 v[136:139], v26 offset:16
	ds_read_b128 v[140:143], v26 offset:8192
	ds_read_b128 v[144:147], v26 offset:8208
	ds_read_b128 v[148:151], v26 offset:16384
	ds_read_b128 v[152:155], v26 offset:16400
	s_waitcnt lgkmcnt(0)
	v_mov_b32_e32 v156, v135
	s_waitcnt lgkmcnt(3)
	v_mov_b32_e32 v158, v143
	v_mov_b32_e32 v162, v139
	s_waitcnt lgkmcnt(1)
	v_mov_b32_e32 v160, v151
	v_mov_b32_e32 v164, v147
	s_waitcnt lgkmcnt(0)
	v_mov_b32_e32 v166, v155
	v_add_u32_e32 v26, 32, v26
	s_waitcnt vmcnt(8)
	v_pk_fma_f32 v[2:3], v[30:31], v[60:61], v[2:3] op_sel_hi:[1,0,1]
	v_pk_fma_f32 v[0:1], v[28:29], v[60:61], v[0:1] op_sel_hi:[1,0,1]
	v_pk_fma_f32 v[6:7], v[30:31], v[68:69], v[6:7] op_sel_hi:[1,0,1]
	v_pk_fma_f32 v[4:5], v[28:29], v[68:69], v[4:5] op_sel_hi:[1,0,1]
	v_pk_fma_f32 v[10:11], v[30:31], v[76:77], v[10:11] op_sel_hi:[1,0,1]
	v_pk_fma_f32 v[8:9], v[28:29], v[76:77], v[8:9] op_sel_hi:[1,0,1]
	v_pk_fma_f32 v[0:1], v[32:33], v[60:61], v[0:1] op_sel:[0,1,0]
	v_pk_fma_f32 v[2:3], v[34:35], v[60:61], v[2:3] op_sel:[0,1,0]
	v_pk_fma_f32 v[4:5], v[32:33], v[68:69], v[4:5] op_sel:[0,1,0]
	v_pk_fma_f32 v[6:7], v[34:35], v[68:69], v[6:7] op_sel:[0,1,0]
	v_pk_fma_f32 v[8:9], v[32:33], v[76:77], v[8:9] op_sel:[0,1,0]
	v_pk_fma_f32 v[10:11], v[34:35], v[76:77], v[10:11] op_sel:[0,1,0]
	v_pk_fma_f32 v[2:3], v[38:39], v[62:63], v[2:3] op_sel_hi:[1,0,1]
	v_pk_fma_f32 v[0:1], v[36:37], v[62:63], v[0:1] op_sel_hi:[1,0,1]
	v_pk_fma_f32 v[6:7], v[38:39], v[70:71], v[6:7] op_sel_hi:[1,0,1]
	v_pk_fma_f32 v[4:5], v[36:37], v[70:71], v[4:5] op_sel_hi:[1,0,1]
	v_pk_fma_f32 v[10:11], v[38:39], v[78:79], v[10:11] op_sel_hi:[1,0,1]
	v_pk_fma_f32 v[8:9], v[36:37], v[78:79], v[8:9] op_sel_hi:[1,0,1]
	v_pk_fma_f32 v[2:3], v[42:43], v[84:85], v[2:3] op_sel_hi:[1,0,1]
	v_pk_fma_f32 v[0:1], v[40:41], v[84:85], v[0:1] op_sel_hi:[1,0,1]
	v_pk_fma_f32 v[6:7], v[42:43], v[86:87], v[6:7] op_sel_hi:[1,0,1]
	v_pk_fma_f32 v[4:5], v[40:41], v[86:87], v[4:5] op_sel_hi:[1,0,1]
	v_pk_fma_f32 v[10:11], v[42:43], v[88:89], v[10:11] op_sel_hi:[1,0,1]
	v_pk_fma_f32 v[8:9], v[40:41], v[88:89], v[8:9] op_sel_hi:[1,0,1]
	v_pk_fma_f32 v[2:3], v[46:47], v[64:65], v[2:3] op_sel_hi:[1,0,1]
	v_pk_fma_f32 v[0:1], v[44:45], v[64:65], v[0:1] op_sel_hi:[1,0,1]
	v_pk_fma_f32 v[6:7], v[46:47], v[72:73], v[6:7] op_sel_hi:[1,0,1]
	v_pk_fma_f32 v[4:5], v[44:45], v[72:73], v[4:5] op_sel_hi:[1,0,1]
	v_pk_fma_f32 v[10:11], v[46:47], v[80:81], v[10:11] op_sel_hi:[1,0,1]
	v_pk_fma_f32 v[8:9], v[44:45], v[80:81], v[8:9] op_sel_hi:[1,0,1]
	v_pk_fma_f32 v[2:3], v[50:51], v[64:65], v[2:3] op_sel:[0,1,0]
	v_pk_fma_f32 v[0:1], v[48:49], v[64:65], v[0:1] op_sel:[0,1,0]
	v_pk_fma_f32 v[6:7], v[50:51], v[72:73], v[6:7] op_sel:[0,1,0]
	v_pk_fma_f32 v[4:5], v[48:49], v[72:73], v[4:5] op_sel:[0,1,0]
	v_pk_fma_f32 v[10:11], v[50:51], v[80:81], v[10:11] op_sel:[0,1,0]
	v_pk_fma_f32 v[8:9], v[48:49], v[80:81], v[8:9] op_sel:[0,1,0]
	v_pk_fma_f32 v[2:3], v[54:55], v[66:67], v[2:3] op_sel_hi:[1,0,1]
	v_pk_fma_f32 v[0:1], v[52:53], v[66:67], v[0:1] op_sel_hi:[1,0,1]
	v_pk_fma_f32 v[6:7], v[54:55], v[74:75], v[6:7] op_sel_hi:[1,0,1]
	v_pk_fma_f32 v[4:5], v[52:53], v[74:75], v[4:5] op_sel_hi:[1,0,1]
	v_pk_fma_f32 v[10:11], v[54:55], v[82:83], v[10:11] op_sel_hi:[1,0,1]
	v_pk_fma_f32 v[8:9], v[52:53], v[82:83], v[8:9] op_sel_hi:[1,0,1]
	v_pk_fma_f32 v[2:3], v[58:59], v[90:91], v[2:3] op_sel_hi:[1,0,1]
	v_pk_fma_f32 v[0:1], v[56:57], v[90:91], v[0:1] op_sel_hi:[1,0,1]
	v_pk_fma_f32 v[6:7], v[58:59], v[92:93], v[6:7] op_sel_hi:[1,0,1]
	v_pk_fma_f32 v[4:5], v[56:57], v[92:93], v[4:5] op_sel_hi:[1,0,1]
	v_pk_fma_f32 v[10:11], v[58:59], v[94:95], v[10:11] op_sel_hi:[1,0,1]
	v_pk_fma_f32 v[8:9], v[56:57], v[94:95], v[8:9] op_sel_hi:[1,0,1]
	s_waitcnt vmcnt(0)
	v_pk_fma_f32 v[2:3], v[102:103], v[132:133], v[2:3] op_sel_hi:[1,0,1]
	v_pk_fma_f32 v[0:1], v[100:101], v[132:133], v[0:1] op_sel_hi:[1,0,1]
	v_pk_fma_f32 v[6:7], v[102:103], v[140:141], v[6:7] op_sel_hi:[1,0,1]
	v_pk_fma_f32 v[4:5], v[100:101], v[140:141], v[4:5] op_sel_hi:[1,0,1]
	v_pk_fma_f32 v[10:11], v[102:103], v[148:149], v[10:11] op_sel_hi:[1,0,1]
	v_pk_fma_f32 v[8:9], v[100:101], v[148:149], v[8:9] op_sel_hi:[1,0,1]
	v_pk_fma_f32 v[0:1], v[104:105], v[132:133], v[0:1] op_sel:[0,1,0]
	v_pk_fma_f32 v[2:3], v[106:107], v[132:133], v[2:3] op_sel:[0,1,0]
	v_pk_fma_f32 v[4:5], v[104:105], v[140:141], v[4:5] op_sel:[0,1,0]
	v_pk_fma_f32 v[6:7], v[106:107], v[140:141], v[6:7] op_sel:[0,1,0]
	v_pk_fma_f32 v[8:9], v[104:105], v[148:149], v[8:9] op_sel:[0,1,0]
	v_pk_fma_f32 v[10:11], v[106:107], v[148:149], v[10:11] op_sel:[0,1,0]
	v_pk_fma_f32 v[2:3], v[110:111], v[134:135], v[2:3] op_sel_hi:[1,0,1]
	v_pk_fma_f32 v[0:1], v[108:109], v[134:135], v[0:1] op_sel_hi:[1,0,1]
	v_pk_fma_f32 v[6:7], v[110:111], v[142:143], v[6:7] op_sel_hi:[1,0,1]
	v_pk_fma_f32 v[4:5], v[108:109], v[142:143], v[4:5] op_sel_hi:[1,0,1]
	v_pk_fma_f32 v[10:11], v[110:111], v[150:151], v[10:11] op_sel_hi:[1,0,1]
	v_pk_fma_f32 v[8:9], v[108:109], v[150:151], v[8:9] op_sel_hi:[1,0,1]
	v_pk_fma_f32 v[2:3], v[114:115], v[156:157], v[2:3] op_sel_hi:[1,0,1]
	v_pk_fma_f32 v[0:1], v[112:113], v[156:157], v[0:1] op_sel_hi:[1,0,1]
	v_pk_fma_f32 v[6:7], v[114:115], v[158:159], v[6:7] op_sel_hi:[1,0,1]
	v_pk_fma_f32 v[4:5], v[112:113], v[158:159], v[4:5] op_sel_hi:[1,0,1]
	v_pk_fma_f32 v[10:11], v[114:115], v[160:161], v[10:11] op_sel_hi:[1,0,1]
	v_pk_fma_f32 v[8:9], v[112:113], v[160:161], v[8:9] op_sel_hi:[1,0,1]
	v_pk_fma_f32 v[2:3], v[118:119], v[136:137], v[2:3] op_sel_hi:[1,0,1]
	v_pk_fma_f32 v[0:1], v[116:117], v[136:137], v[0:1] op_sel_hi:[1,0,1]
	v_pk_fma_f32 v[6:7], v[118:119], v[144:145], v[6:7] op_sel_hi:[1,0,1]
	v_pk_fma_f32 v[4:5], v[116:117], v[144:145], v[4:5] op_sel_hi:[1,0,1]
	v_pk_fma_f32 v[10:11], v[118:119], v[152:153], v[10:11] op_sel_hi:[1,0,1]
	v_pk_fma_f32 v[8:9], v[116:117], v[152:153], v[8:9] op_sel_hi:[1,0,1]
	v_pk_fma_f32 v[2:3], v[122:123], v[136:137], v[2:3] op_sel:[0,1,0]
	v_pk_fma_f32 v[0:1], v[120:121], v[136:137], v[0:1] op_sel:[0,1,0]
	v_pk_fma_f32 v[6:7], v[122:123], v[144:145], v[6:7] op_sel:[0,1,0]
	v_pk_fma_f32 v[4:5], v[120:121], v[144:145], v[4:5] op_sel:[0,1,0]
	v_pk_fma_f32 v[10:11], v[122:123], v[152:153], v[10:11] op_sel:[0,1,0]
	v_pk_fma_f32 v[8:9], v[120:121], v[152:153], v[8:9] op_sel:[0,1,0]
	v_pk_fma_f32 v[2:3], v[126:127], v[138:139], v[2:3] op_sel_hi:[1,0,1]
	v_pk_fma_f32 v[0:1], v[124:125], v[138:139], v[0:1] op_sel_hi:[1,0,1]
	v_pk_fma_f32 v[6:7], v[126:127], v[146:147], v[6:7] op_sel_hi:[1,0,1]
	v_pk_fma_f32 v[4:5], v[124:125], v[146:147], v[4:5] op_sel_hi:[1,0,1]
	v_pk_fma_f32 v[10:11], v[126:127], v[154:155], v[10:11] op_sel_hi:[1,0,1]
	v_pk_fma_f32 v[8:9], v[124:125], v[154:155], v[8:9] op_sel_hi:[1,0,1]
	v_pk_fma_f32 v[2:3], v[130:131], v[162:163], v[2:3] op_sel_hi:[1,0,1]
	v_pk_fma_f32 v[0:1], v[128:129], v[162:163], v[0:1] op_sel_hi:[1,0,1]
	v_pk_fma_f32 v[6:7], v[130:131], v[164:165], v[6:7] op_sel_hi:[1,0,1]
	v_pk_fma_f32 v[4:5], v[128:129], v[164:165], v[4:5] op_sel_hi:[1,0,1]
	v_pk_fma_f32 v[10:11], v[130:131], v[166:167], v[10:11] op_sel_hi:[1,0,1]
	v_pk_fma_f32 v[8:9], v[128:129], v[166:167], v[8:9] op_sel_hi:[1,0,1]
	s_cbranch_scc0 .LBB0_29
	ds_write_b128 v24, v[0:3] offset:24576
	ds_write_b128 v24, v[4:7] offset:25600
	ds_write_b128 v24, v[8:11] offset:26624
	s_waitcnt lgkmcnt(0)
	s_barrier
	s_and_saveexec_b64 s[18:19], s[4:5]
	s_cbranch_execz .LBB0_27
	s_cmp_eq_u32 s20, 0
	s_mul_i32 s17, s16, 0x1800
	s_cselect_b64 s[20:21], -1, 0
	s_add_i32 s17, s17, s44
	v_add_u32_sdwa v2, s17, v22 dst_sel:DWORD dst_unused:UNUSED_PAD src0_sel:DWORD src1_sel:BYTE_0
	v_ashrrev_i32_e32 v3, 31, v2
	s_mul_i32 s16, s16, 3
	v_lshl_add_u64 v[0:1], s[6:7], 2, v[16:17]
	v_lshl_add_u64 v[2:3], v[2:3], 2, s[22:23]
	s_mov_b64 s[6:7], 0
	v_mov_b32_e32 v4, v22
	s_branch .LBB0_33

.LBB0_35:
	v_readfirstlane_b32 s3, v247
	s_cmp_lg_u32 s3, 0
	s_cbranch_scc1 .Lgemv_back
	v_readlane_b32 s4, v253, 0
	v_readlane_b32 s5, v253, 1
	s_load_dword s3, s[4:5], 0x0
	s_nop 0
	s_load_dword s4, s[4:5], 0x10
	s_mov_b64 s[6:7], src_shared_base
	s_add_u32 s6, s28, 0x1dfdb6b0
	s_addc_u32 s33, s29, 0
	s_add_u32 s46, s28, 0x5000000
	s_addc_u32 s47, s29, 0
	s_waitcnt lgkmcnt(0)
	s_lshr_b32 s4, s4, 16
	s_cmp_lg_u32 s4, 0
	s_cselect_b64 s[4:5], -1, 0
	s_cmp_lg_u64 s[4:5], 0
	s_addc_u32 s3, s3, 0
	s_mov_b32 s17, 0
	s_cmpk_lg_i32 s3, 0x100
	s_cselect_b64 s[18:19], -1, 0
	v_mov_b32_e32 v10, 1
	s_add_i32 s48, 0, 0x1c200
	s_movk_i32 s49, 0x380
	v_mov_b32_e32 v1, 0
	s_movk_i32 s50, 0x204
	s_movk_i32 s51, 0x1020
	s_movk_i32 s57, 0x27f
	s_mov_b32 s58, 0x66666667
	s_movk_i32 s59, 0x37f
	v_mov_b32_e32 v11, 0x4080
	v_mov_b32_e32 v12, 0x8100
	s_mov_b32 s16, s17
	s_branch .LBB0_37

.LBB0_246:
	s_waitcnt vmcnt(0) lgkmcnt(0)
	s_barrier
	s_cmp_gt_u32 s35, 2
	s_cbranch_scc1 .Lgemv_skip
	s_cmp_lt_u32 s2, 0xc0
	s_cbranch_scc1 .Lgemv_skip
	s_cmp_gt_u32 s2, 0xef
	s_cbranch_scc1 .Lgemv_skip
	v_writelane_b32 v246, s0, 0
	v_writelane_b32 v246, s1, 1
	v_writelane_b32 v246, s2, 2
	v_writelane_b32 v246, s3, 3
	v_writelane_b32 v246, s4, 4
	v_writelane_b32 v246, s5, 5
	v_writelane_b32 v246, s6, 6
	v_writelane_b32 v246, s7, 7
	v_writelane_b32 v246, s8, 8
	v_writelane_b32 v246, s9, 9
	v_writelane_b32 v246, s10, 10
	v_writelane_b32 v246, s11, 11
	v_writelane_b32 v246, s12, 12
	v_writelane_b32 v246, s13, 13
	v_writelane_b32 v246, s14, 14
	v_writelane_b32 v246, s15, 15
	v_writelane_b32 v246, s16, 16
	v_writelane_b32 v246, s17, 17
	v_writelane_b32 v246, s18, 18
	v_writelane_b32 v246, s19, 19
	v_writelane_b32 v246, s20, 20
	v_writelane_b32 v246, s21, 21
	v_writelane_b32 v246, s22, 22
	v_writelane_b32 v246, s23, 23
	v_writelane_b32 v246, s28, 24
	v_writelane_b32 v246, s29, 25
	v_writelane_b32 v246, s30, 26
	v_writelane_b32 v246, s31, 27
	v_writelane_b32 v246, s33, 28
	v_writelane_b32 v246, s34, 29
	v_writelane_b32 v246, s35, 30
	v_writelane_b32 v246, s36, 31
	v_writelane_b32 v246, s37, 32
	v_writelane_b32 v246, s38, 33
	v_writelane_b32 v246, s39, 34
	v_writelane_b32 v246, s40, 35
	v_writelane_b32 v246, s41, 36
	v_writelane_b32 v246, s42, 37
	v_writelane_b32 v246, s43, 38
	v_writelane_b32 v246, s44, 39
	v_writelane_b32 v246, s64, 40
	v_writelane_b32 v246, s65, 41
	v_writelane_b32 v246, s66, 42
	v_writelane_b32 v246, s67, 43
	v_mov_b32_e32 v247, 1
	s_mul_i32 s3, s35, 48
	s_addk_i32 s3, 0x30
	s_sub_i32 s2, s2, 0xc0
	s_add_i32 s2, s2, s3
	v_readlane_b32 s0, v253, 0
	v_readlane_b32 s1, v253, 1
	s_sub_u32 s0, s0, 0xb0
	s_subb_u32 s1, s1, 0
	s_load_dwordx4 s[64:67], s[0:1], 0x90
	s_waitcnt lgkmcnt(0)
	s_branch .Lgemv_entry
.Lgemv_back:
	v_readlane_b32 s0, v246, 0
	v_readlane_b32 s1, v246, 1
	v_readlane_b32 s2, v246, 2
	v_readlane_b32 s3, v246, 3
	v_readlane_b32 s4, v246, 4
	v_readlane_b32 s5, v246, 5
	v_readlane_b32 s6, v246, 6
	v_readlane_b32 s7, v246, 7
	v_readlane_b32 s8, v246, 8
	v_readlane_b32 s9, v246, 9
	v_readlane_b32 s10, v246, 10
	v_readlane_b32 s11, v246, 11
	v_readlane_b32 s12, v246, 12
	v_readlane_b32 s13, v246, 13
	v_readlane_b32 s14, v246, 14
	v_readlane_b32 s15, v246, 15
	v_readlane_b32 s16, v246, 16
	v_readlane_b32 s17, v246, 17
	v_readlane_b32 s18, v246, 18
	v_readlane_b32 s19, v246, 19
	v_readlane_b32 s20, v246, 20
	v_readlane_b32 s21, v246, 21
	v_readlane_b32 s22, v246, 22
	v_readlane_b32 s23, v246, 23
	v_readlane_b32 s28, v246, 24
	v_readlane_b32 s29, v246, 25
	v_readlane_b32 s30, v246, 26
	v_readlane_b32 s31, v246, 27
	v_readlane_b32 s33, v246, 28
	v_readlane_b32 s34, v246, 29
	v_readlane_b32 s35, v246, 30
	v_readlane_b32 s36, v246, 31
	v_readlane_b32 s37, v246, 32
	v_readlane_b32 s38, v246, 33
	v_readlane_b32 s39, v246, 34
	v_readlane_b32 s40, v246, 35
	v_readlane_b32 s41, v246, 36
	v_readlane_b32 s42, v246, 37
	v_readlane_b32 s43, v246, 38
	v_readlane_b32 s44, v246, 39
	v_readlane_b32 s64, v246, 40
	v_readlane_b32 s65, v246, 41
	v_readlane_b32 s66, v246, 42
	v_readlane_b32 s67, v246, 43
	v_mov_b32_e32 v1, 0
	s_nop 1
.Lgemv_skip:
.LBB0_247:
	v_readlane_b32 s0, v254, 39
	s_add_i32 s22, s0, 1
	v_readlane_b32 s0, v253, 6
	v_readlane_b32 s1, v253, 7
	s_and_b64 s[18:19], s[18:19], s[0:1]
	s_cmp_lt_i32 s22, s53
	s_cselect_b64 s[0:1], -1, 0
	s_and_b64 s[18:19], s[18:19], s[0:1]
	s_andn2_b64 vcc, exec, s[18:19]
	s_cbranch_vccnz .LBB0_301
	s_waitcnt vmcnt(0)
	s_barrier
	s_mov_b64 s[18:19], exec
	v_readlane_b32 s24, v253, 2
	v_readlane_b32 s25, v253, 3
	s_and_b64 s[24:25], s[18:19], s[24:25]
	s_mov_b64 exec, s[24:25]
	s_cbranch_execz .LBB0_300
	v_readlane_b32 s23, v254, 50
	s_waitcnt vmcnt(0) expcnt(0) lgkmcnt(0)
	s_nop 0
	v_mov_b32_e32 v0, s23
	ds_read_b32 v3, v0
	v_readlane_b32 s23, v254, 51
	s_waitcnt lgkmcnt(0)
	v_cmp_ne_u32_e32 vcc, 0, v3
	v_mov_b32_e32 v0, s23
	ds_read_b32 v2, v0
	s_cbranch_vccnz .LBB0_264
	s_mov_b32 s23, 1
	s_branch .LBB0_252

.LBB0_563:
	s_cmp_lt_i32 s18, s52
	s_cselect_b64 s[18:19], -1, 0
	s_xor_b64 s[0:1], s[0:1], -1
	s_or_b64 s[0:1], s[18:19], s[0:1]
	s_and_b64 vcc, exec, s[0:1]
	s_cbranch_vccnz .LBB0_768
	s_mov_b64 s[0:1], s[64:65]
	s_add_u32 s24, s66, 0xa048000
	s_addc_u32 s25, s67, 0
	v_readlane_b32 s18, v253, 60
	s_add_u32 s64, s66, 0x11848000
	v_readlane_b32 s19, v253, 61
	s_addc_u32 s65, s67, 0
	s_mov_b64 s[0:1], -1
	s_and_b64 vcc, exec, s[18:19]
	s_cbranch_vccz .LBB0_743
	s_add_u32 s50, s66, 0x1a848000
	s_addc_u32 s51, s67, 0
	v_readlane_b32 s0, v255, 21
	s_add_u32 s54, s66, 0x1b448000
	s_addc_u32 s55, s67, 0
	s_lshl_b32 s63, s0, 8
	v_readlane_b32 s22, v254, 32
	s_mul_i32 s88, s0, 12
	s_add_u32 s18, s66, 0x1b548000
	v_readlane_b32 s23, v254, 33
	s_addc_u32 s19, s67, 0
	s_lshl_b32 s37, s0, 2
	s_mov_b64 s[0:1], -1
	s_and_b64 vcc, exec, s[22:23]
	v_writelane_b32 v255, s88, 32
	s_cbranch_vccz .LBB0_639
	v_readlane_b32 s0, v254, 0
	v_readlane_b32 s1, v254, 1
	s_andn2_b64 vcc, exec, s[0:1]
	s_cbranch_vccnz .LBB0_638
	v_readlane_b32 s22, v254, 40
	s_branch .LBB0_570
.Lisland_end:
	s_branch .LBB0_983
.Lisland_196:
	s_branch .LBB0_196
.LBB0_568:
	v_mov_b32_e32 v16, v1
	v_mov_b32_e32 v17, v1
	v_mov_b32_e32 v2, v1
	v_mov_b32_e32 v3, v1
	v_mov_b32_e32 v4, v1
	v_mov_b32_e32 v5, v1
	v_mov_b32_e32 v6, v1
	v_mov_b32_e32 v7, v1
	v_mov_b32_e32 v8, v1
	v_mov_b32_e32 v9, v1
	v_mov_b32_e32 v10, v1
	v_mov_b32_e32 v11, v1
	v_mov_b32_e32 v12, v1
	v_mov_b32_e32 v13, v1
	v_mov_b32_e32 v14, v1
	v_mov_b32_e32 v15, v1
	v_mov_b64_e32 v[32:33], v[16:17]
	v_mov_b64_e32 v[48:49], v[16:17]
	v_mov_b64_e32 v[64:65], v[16:17]
	v_mov_b64_e32 v[30:31], v[14:15]
	v_mov_b64_e32 v[28:29], v[12:13]
	v_mov_b64_e32 v[26:27], v[10:11]
	v_mov_b64_e32 v[24:25], v[8:9]
	v_mov_b64_e32 v[22:23], v[6:7]
	v_mov_b64_e32 v[20:21], v[4:5]
	v_mov_b64_e32 v[18:19], v[2:3]
	v_mov_b64_e32 v[46:47], v[14:15]
	v_mov_b64_e32 v[44:45], v[12:13]
	v_mov_b64_e32 v[42:43], v[10:11]
	v_mov_b64_e32 v[40:41], v[8:9]
	v_mov_b64_e32 v[38:39], v[6:7]
	v_mov_b64_e32 v[36:37], v[4:5]
	v_mov_b64_e32 v[34:35], v[2:3]
	v_mov_b64_e32 v[62:63], v[14:15]
	v_mov_b64_e32 v[60:61], v[12:13]
	v_mov_b64_e32 v[58:59], v[10:11]
	v_mov_b64_e32 v[56:57], v[8:9]
	v_mov_b64_e32 v[54:55], v[6:7]
	v_mov_b64_e32 v[52:53], v[4:5]
	v_mov_b64_e32 v[50:51], v[2:3]
